# isel scores: head-weight registers rotated by one within each group of 16 so the two VGPR sources of every fmac sit in different register banks
# speedup vs baseline: 1.0035x; 1.0002x over previous
.LBB0_330:
	s_and_b32 s2, s45, 0xff
	s_ashr_i32 s1, s45, 9
	s_and_b32 s0, s45, 0x100
	s_xor_b32 s3, s2, 0x1ff
	s_cmp_eq_u32 s0, 0
	v_mov_b32_e32 v13, v212
	s_cselect_b32 s2, s2, s3
	s_lshl_b32 s29, s2, 3
	v_readfirstlane_b32 s0, v13
	s_lshl_b32 s49, s1, 12
	s_lshr_b32 s34, s2, 2
	s_ashr_i32 s0, s0, 6
	s_cmp_gt_i32 s0, s34
	v_and_b32_e32 v221, 63, v13
	s_cbranch_scc1 .LBB0_335
	s_or_b32 s6, s29, s49
	s_lshl_b32 s2, s2, 11
	s_lshl_b32 s4, s6, 1
	s_and_b32 s35, s2, 0xf000
	s_or_b32 s2, s4, 1
	s_ashr_i32 s3, s2, 31
	s_lshl_b64 s[38:39], s[2:3], 10
	s_or_b32 s2, s4, 2
	s_ashr_i32 s3, s2, 31
	s_lshl_b64 s[40:41], s[2:3], 10
	s_or_b32 s2, s4, 3
	s_ashr_i32 s3, s2, 31
	s_lshl_b64 s[42:43], s[2:3], 10
	s_ashr_i32 s2, s6, 8
	s_mulk_i32 s2, 0x49
	s_ashr_i32 s3, s2, 31
	s_lshl_b64 s[30:31], s[2:3], 17
	s_or_b32 s2, s4, 4
	s_ashr_i32 s3, s2, 31
	s_lshl_b64 s[20:21], s[2:3], 10
	s_or_b32 s2, s4, 5
	s_ashr_i32 s3, s2, 31
	s_lshl_b64 s[22:23], s[2:3], 10
	s_or_b32 s2, s4, 6
	s_ashr_i32 s3, s2, 31
	s_lshl_b64 s[24:25], s[2:3], 10
	s_or_b32 s2, s4, 7
	s_ashr_i32 s3, s2, 31
	s_lshl_b64 s[26:27], s[2:3], 10
	s_or_b32 s2, s4, 8
	s_ashr_i32 s3, s2, 31
	s_lshl_b64 s[12:13], s[2:3], 10
	s_or_b32 s2, s4, 9
	s_ashr_i32 s3, s2, 31
	s_lshl_b64 s[14:15], s[2:3], 10
	s_or_b32 s2, s4, 10
	s_ashr_i32 s5, s4, 31
	s_ashr_i32 s3, s2, 31
	s_lshl_b64 s[36:37], s[4:5], 10
	s_lshl_b64 s[16:17], s[2:3], 10
	s_or_b32 s2, s4, 11
	s_waitcnt vmcnt(0)
	s_ashr_i32 s3, s2, 31
	s_lshl_b64 s[18:19], s[2:3], 10
	s_or_b32 s2, s4, 12
	s_or_b32 s6, s4, 13
	s_or_b32 s8, s4, 14
	s_or_b32 s4, s4, 15
	s_ashr_i32 s5, s4, 31
	s_lshl_b64 s[10:11], s[4:5], 10
	s_lshl_b32 s4, s1, 7
	s_ashr_i32 s3, s2, 31
	s_ashr_i32 s7, s6, 31
	s_ashr_i32 s9, s8, 31
	s_ashr_i32 s5, s4, 31
	s_lshl_b64 s[2:3], s[2:3], 10
	s_lshl_b64 s[6:7], s[6:7], 10
	s_lshl_b64 s[8:9], s[8:9], 10
	s_lshl_b64 s[4:5], s[4:5], 12
	v_readlane_b32 s36, v237, 5
	v_readlane_b32 s37, v237, 6
	s_add_u32 s30, s36, s30
	s_addc_u32 s31, s37, s31
	s_mov_b32 s1, 0x1bb00000
	s_mov_b64 s[30:31], 0x1bb00800
	s_mov_b32 s30, 0x3d000000
	v_readlane_b32 s36, v237, 46
	s_movk_i32 s41, 0x3fff
	s_mov_b32 s40, 0x800000
	s_movk_i32 s39, 0x1e0
	v_readlane_b32 s38, v237, 45
	v_readlane_b32 s37, v237, 47
	s_mov_b64 s[20:21], 0x1bb00880
	s_mov_b64 s[12:13], 0x1bb00900
	s_mov_b64 s[2:3], 0x1bb00980
	v_readlane_b32 s2, v239, 12
	v_readlane_b32 s3, v239, 13
	s_add_u32 s2, s2, s4
	s_addc_u32 s3, s3, s5
	s_ashr_i32 s1, s0, 31
	s_lshl_b64 s[2:3], s[0:1], 12
	s_lshl_b32 s1, s0, 7
	s_add_i32 s1, 0, 0x10000
	s_add_u32 s1, s2, s4
	s_addc_u32 s3, s3, s5
	v_readlane_b32 s2, v237, 3
	s_add_u32 s2, s2, s1
	v_readlane_b32 s1, v237, 4
	s_addc_u32 s3, s1, s3
	s_mov_b32 s1, s0
	v_lshlrev_b32_e32 v0, 4, v221
	v_lshrrev_b32_e32 v12, 5, v221
	v_and_b32_e32 v4, 31, v13
	s_or_b32 s2, s29, s49
	v_readlane_b32 s4, v237, 5
	v_readlane_b32 s5, v237, 6
	s_lshr_b32 s3, s2, 8
	s_mulk_i32 s3, 0x49
	s_lshl_b32 s3, s3, 17
	s_add_u32 s3, s3, 0x1bb00000
	s_add_u32 s4, s4, s3
	s_addc_u32 s5, s5, 0
	s_lshl_b32 s3, s29, 8
	s_and_b32 s3, s3, 0xf000
	v_or_b32_e32 v222, s29, v12
	v_lshlrev_b32_e32 v2, 5, v222
	v_and_b32_e32 v2, 0x120, v2
	v_or_b32_e32 v2, s3, v2
	v_lshlrev_b32_e32 v2, 1, v2
	v_mov_b32_e32 v3, v1
	v_lshl_add_u64 v[6:7], s[4:5], 0, v[2:3]
	global_load_dwordx4 v[18:21], v[6:7], off offset:2048
	global_load_dwordx4 v[22:25], v[6:7], off offset:2064
	global_load_dwordx4 v[26:29], v[6:7], off offset:2176
	global_load_dwordx4 v[30:33], v[6:7], off offset:2192
	global_load_dwordx4 v[34:37], v[6:7], off offset:2304
	global_load_dwordx4 v[38:41], v[6:7], off offset:2320
	global_load_dwordx4 v[42:45], v[6:7], off offset:2432
	global_load_dwordx4 v[46:49], v[6:7], off offset:2448
	s_lshl_b32 s3, s2, 11
	s_add_u32 s4, s82, s3
	s_addc_u32 s5, s83, 0
	s_add_u32 s4, s4, 0x1000
	s_addc_u32 s5, s5, 0
	v_lshl_add_u64 v[8:9], s[4:5], 0, v[0:1]
	s_add_u32 s4, s4, 0x2000
	s_addc_u32 s5, s5, 0
	v_lshl_add_u64 v[10:11], s[4:5], 0, v[0:1]
	global_load_dwordx4 v[66:69], v[8:9], off offset:-4096
	global_load_dwordx4 v[70:73], v[8:9], off offset:-3072
	global_load_dwordx4 v[74:77], v[8:9], off offset:-2048
	global_load_dwordx4 v[78:81], v[8:9], off offset:-1024
	global_load_dwordx4 v[82:85], v[8:9], off
	global_load_dwordx4 v[86:89], v[8:9], off offset:1024
	global_load_dwordx4 v[90:93], v[8:9], off offset:2048
	global_load_dwordx4 v[94:97], v[8:9], off offset:3072
	global_load_dwordx4 v[98:101], v[10:11], off offset:-4096
	global_load_dwordx4 v[102:105], v[10:11], off offset:-3072
	global_load_dwordx4 v[106:109], v[10:11], off offset:-2048
	global_load_dwordx4 v[110:113], v[10:11], off offset:-1024
	global_load_dwordx4 v[114:117], v[10:11], off
	global_load_dwordx4 v[118:121], v[10:11], off offset:1024
	global_load_dwordx4 v[122:125], v[10:11], off offset:2048
	global_load_dwordx4 v[126:129], v[10:11], off offset:3072
	v_readlane_b32 s4, v239, 12
	v_readlane_b32 s5, v239, 13
	s_lshl_b32 s3, s49, 7
	s_lshl_b32 s2, s0, 12
	s_add_u32 s3, s3, s2
	s_add_u32 s4, s4, s3
	s_addc_u32 s5, s5, 0
	v_lshl_add_u64 v[2:3], s[4:5], 0, v[0:1]
	global_load_dwordx4 v[130:133], v[2:3], off
	global_load_dwordx4 v[134:137], v[2:3], off offset:1024
	global_load_dwordx4 v[138:141], v[2:3], off offset:2048
	global_load_dwordx4 v[142:145], v[2:3], off offset:3072
	s_add_u32 s4, s4, 0x8800
	s_addc_u32 s5, s5, 0
	v_lshl_add_u64 v[210:211], s[4:5], 0, v[0:1]
	v_or_b32_e32 v223, 2, v222
	v_or_b32_e32 v224, 4, v222
	v_or_b32_e32 v225, 6, v222
	s_lshl_b32 s2, s0, 7
	v_lshlrev_b32_e32 v2, 14, v12
	v_lshl_or_b32 v2, v4, 2, v2
	v_add_u32_e32 v2, s2, v2
	v_add_u32_e32 v227, 0x10000, v2
	v_lshl_or_b32 v226, s0, 5, v4
	s_waitcnt vmcnt(20)
	v_and_b32_e32 v3, 0xffff0000, v18
	v_lshlrev_b32_e32 v2, 16, v18
	v_mul_f32_e32 v148, s30, v3
	v_mul_f32_e32 v147, s30, v2
	v_and_b32_e32 v3, 0xffff0000, v19
	v_lshlrev_b32_e32 v2, 16, v19
	v_mul_f32_e32 v150, s30, v3
	v_mul_f32_e32 v149, s30, v2
	v_and_b32_e32 v3, 0xffff0000, v20
	v_lshlrev_b32_e32 v2, 16, v20
	v_mul_f32_e32 v152, s30, v3
	v_mul_f32_e32 v151, s30, v2
	v_and_b32_e32 v3, 0xffff0000, v21
	v_lshlrev_b32_e32 v2, 16, v21
	v_mul_f32_e32 v154, s30, v3
	v_mul_f32_e32 v153, s30, v2
	v_and_b32_e32 v3, 0xffff0000, v22
	v_lshlrev_b32_e32 v2, 16, v22
	v_mul_f32_e32 v156, s30, v3
	v_mul_f32_e32 v155, s30, v2
	v_and_b32_e32 v3, 0xffff0000, v23
	v_lshlrev_b32_e32 v2, 16, v23
	v_mul_f32_e32 v158, s30, v3
	v_mul_f32_e32 v157, s30, v2
	v_and_b32_e32 v3, 0xffff0000, v24
	v_lshlrev_b32_e32 v2, 16, v24
	v_mul_f32_e32 v160, s30, v3
	v_mul_f32_e32 v159, s30, v2
	v_and_b32_e32 v3, 0xffff0000, v25
	v_lshlrev_b32_e32 v2, 16, v25
	v_mul_f32_e32 v146, s30, v3
	v_mul_f32_e32 v161, s30, v2
	v_and_b32_e32 v3, 0xffff0000, v26
	v_lshlrev_b32_e32 v2, 16, v26
	v_mul_f32_e32 v164, s30, v3
	v_mul_f32_e32 v163, s30, v2
	v_and_b32_e32 v3, 0xffff0000, v27
	v_lshlrev_b32_e32 v2, 16, v27
	v_mul_f32_e32 v166, s30, v3
	v_mul_f32_e32 v165, s30, v2
	v_and_b32_e32 v3, 0xffff0000, v28
	v_lshlrev_b32_e32 v2, 16, v28
	v_mul_f32_e32 v168, s30, v3
	v_mul_f32_e32 v167, s30, v2
	v_and_b32_e32 v3, 0xffff0000, v29
	v_lshlrev_b32_e32 v2, 16, v29
	v_mul_f32_e32 v170, s30, v3
	v_mul_f32_e32 v169, s30, v2
	v_and_b32_e32 v3, 0xffff0000, v30
	v_lshlrev_b32_e32 v2, 16, v30
	v_mul_f32_e32 v172, s30, v3
	v_mul_f32_e32 v171, s30, v2
	v_and_b32_e32 v3, 0xffff0000, v31
	v_lshlrev_b32_e32 v2, 16, v31
	v_mul_f32_e32 v174, s30, v3
	v_mul_f32_e32 v173, s30, v2
	v_and_b32_e32 v3, 0xffff0000, v32
	v_lshlrev_b32_e32 v2, 16, v32
	v_mul_f32_e32 v176, s30, v3
	v_mul_f32_e32 v175, s30, v2
	v_and_b32_e32 v3, 0xffff0000, v33
	v_lshlrev_b32_e32 v2, 16, v33
	v_mul_f32_e32 v162, s30, v3
	v_mul_f32_e32 v177, s30, v2
	v_and_b32_e32 v3, 0xffff0000, v34
	v_lshlrev_b32_e32 v2, 16, v34
	v_mul_f32_e32 v180, s30, v3
	v_mul_f32_e32 v179, s30, v2
	v_and_b32_e32 v3, 0xffff0000, v35
	v_lshlrev_b32_e32 v2, 16, v35
	v_mul_f32_e32 v182, s30, v3
	v_mul_f32_e32 v181, s30, v2
	v_and_b32_e32 v3, 0xffff0000, v36
	v_lshlrev_b32_e32 v2, 16, v36
	v_mul_f32_e32 v184, s30, v3
	v_mul_f32_e32 v183, s30, v2
	v_and_b32_e32 v3, 0xffff0000, v37
	v_lshlrev_b32_e32 v2, 16, v37
	v_mul_f32_e32 v186, s30, v3
	v_mul_f32_e32 v185, s30, v2
	v_and_b32_e32 v3, 0xffff0000, v38
	v_lshlrev_b32_e32 v2, 16, v38
	v_mul_f32_e32 v188, s30, v3
	v_mul_f32_e32 v187, s30, v2
	v_and_b32_e32 v3, 0xffff0000, v39
	v_lshlrev_b32_e32 v2, 16, v39
	v_mul_f32_e32 v190, s30, v3
	v_mul_f32_e32 v189, s30, v2
	v_and_b32_e32 v3, 0xffff0000, v40
	v_lshlrev_b32_e32 v2, 16, v40
	v_mul_f32_e32 v192, s30, v3
	v_mul_f32_e32 v191, s30, v2
	v_and_b32_e32 v3, 0xffff0000, v41
	v_lshlrev_b32_e32 v2, 16, v41
	v_mul_f32_e32 v178, s30, v3
	v_mul_f32_e32 v193, s30, v2
	v_and_b32_e32 v3, 0xffff0000, v42
	v_lshlrev_b32_e32 v2, 16, v42
	v_mul_f32_e32 v196, s30, v3
	v_mul_f32_e32 v195, s30, v2
	v_and_b32_e32 v3, 0xffff0000, v43
	v_lshlrev_b32_e32 v2, 16, v43
	v_mul_f32_e32 v198, s30, v3
	v_mul_f32_e32 v197, s30, v2
	v_and_b32_e32 v3, 0xffff0000, v44
	v_lshlrev_b32_e32 v2, 16, v44
	v_mul_f32_e32 v200, s30, v3
	v_mul_f32_e32 v199, s30, v2
	v_and_b32_e32 v3, 0xffff0000, v45
	v_lshlrev_b32_e32 v2, 16, v45
	v_mul_f32_e32 v202, s30, v3
	v_mul_f32_e32 v201, s30, v2
	v_and_b32_e32 v3, 0xffff0000, v46
	v_lshlrev_b32_e32 v2, 16, v46
	v_mul_f32_e32 v204, s30, v3
	v_mul_f32_e32 v203, s30, v2
	v_and_b32_e32 v3, 0xffff0000, v47
	v_lshlrev_b32_e32 v2, 16, v47
	v_mul_f32_e32 v206, s30, v3
	v_mul_f32_e32 v205, s30, v2
	v_and_b32_e32 v3, 0xffff0000, v48
	v_lshlrev_b32_e32 v2, 16, v48
	v_mul_f32_e32 v208, s30, v3
	v_mul_f32_e32 v207, s30, v2
	v_and_b32_e32 v3, 0xffff0000, v49
	v_lshlrev_b32_e32 v2, 16, v49
	v_mul_f32_e32 v194, s30, v3
	v_mul_f32_e32 v209, s30, v2
	s_branch .LBB0_333
.LBB0_332:
	s_nop 7
	v_max_f32_e32 v50, 0, v50
	v_max_f32_e32 v34, 0, v34
	v_max_f32_e32 v18, 0, v18
	v_max_f32_e32 v2, 0, v2
	v_mul_f32_e32 v228, v147, v50
	v_mul_f32_e32 v229, v163, v34
	v_mul_f32_e32 v230, v179, v18
	v_mul_f32_e32 v231, v195, v2
	v_max_f32_e32 v51, 0, v51
	v_max_f32_e32 v35, 0, v35
	v_max_f32_e32 v19, 0, v19
	v_max_f32_e32 v3, 0, v3
	v_fmac_f32_e32 v228, v148, v51
	v_fmac_f32_e32 v229, v164, v35
	v_fmac_f32_e32 v230, v180, v19
	v_fmac_f32_e32 v231, v196, v3
	v_max_f32_e32 v52, 0, v52
	v_max_f32_e32 v36, 0, v36
	v_max_f32_e32 v20, 0, v20
	v_max_f32_e32 v4, 0, v4
	v_fmac_f32_e32 v228, v149, v52
	v_fmac_f32_e32 v229, v165, v36
	v_fmac_f32_e32 v230, v181, v20
	v_fmac_f32_e32 v231, v197, v4
	v_max_f32_e32 v53, 0, v53
	v_max_f32_e32 v37, 0, v37
	v_max_f32_e32 v21, 0, v21
	v_max_f32_e32 v5, 0, v5
	v_fmac_f32_e32 v228, v150, v53
	v_fmac_f32_e32 v229, v166, v37
	v_fmac_f32_e32 v230, v182, v21
	v_fmac_f32_e32 v231, v198, v5
	v_max_f32_e32 v54, 0, v54
	v_max_f32_e32 v38, 0, v38
	v_max_f32_e32 v22, 0, v22
	v_max_f32_e32 v6, 0, v6
	v_fmac_f32_e32 v228, v151, v54
	v_fmac_f32_e32 v229, v167, v38
	v_fmac_f32_e32 v230, v183, v22
	v_fmac_f32_e32 v231, v199, v6
	v_max_f32_e32 v55, 0, v55
	v_max_f32_e32 v39, 0, v39
	v_max_f32_e32 v23, 0, v23
	v_max_f32_e32 v7, 0, v7
	v_fmac_f32_e32 v228, v152, v55
	v_fmac_f32_e32 v229, v168, v39
	v_fmac_f32_e32 v230, v184, v23
	v_fmac_f32_e32 v231, v200, v7
	v_max_f32_e32 v56, 0, v56
	v_max_f32_e32 v40, 0, v40
	v_max_f32_e32 v24, 0, v24
	v_max_f32_e32 v8, 0, v8
	v_fmac_f32_e32 v228, v153, v56
	v_fmac_f32_e32 v229, v169, v40
	v_fmac_f32_e32 v230, v185, v24
	v_fmac_f32_e32 v231, v201, v8
	v_max_f32_e32 v57, 0, v57
	v_max_f32_e32 v41, 0, v41
	v_max_f32_e32 v25, 0, v25
	v_max_f32_e32 v9, 0, v9
	v_fmac_f32_e32 v228, v154, v57
	v_fmac_f32_e32 v229, v170, v41
	v_fmac_f32_e32 v230, v186, v25
	v_fmac_f32_e32 v231, v202, v9
	v_max_f32_e32 v58, 0, v58
	v_max_f32_e32 v42, 0, v42
	v_max_f32_e32 v26, 0, v26
	v_max_f32_e32 v10, 0, v10
	v_fmac_f32_e32 v228, v155, v58
	v_fmac_f32_e32 v229, v171, v42
	v_fmac_f32_e32 v230, v187, v26
	v_fmac_f32_e32 v231, v203, v10
	v_max_f32_e32 v59, 0, v59
	v_max_f32_e32 v43, 0, v43
	v_max_f32_e32 v27, 0, v27
	v_max_f32_e32 v11, 0, v11
	v_fmac_f32_e32 v228, v156, v59
	v_fmac_f32_e32 v229, v172, v43
	v_fmac_f32_e32 v230, v188, v27
	v_fmac_f32_e32 v231, v204, v11
	v_max_f32_e32 v60, 0, v60
	v_max_f32_e32 v44, 0, v44
	v_max_f32_e32 v28, 0, v28
	v_max_f32_e32 v12, 0, v12
	v_fmac_f32_e32 v228, v157, v60
	v_fmac_f32_e32 v229, v173, v44
	v_fmac_f32_e32 v230, v189, v28
	v_fmac_f32_e32 v231, v205, v12
	v_max_f32_e32 v61, 0, v61
	v_max_f32_e32 v45, 0, v45
	v_max_f32_e32 v29, 0, v29
	v_max_f32_e32 v13, 0, v13
	v_fmac_f32_e32 v228, v158, v61
	v_fmac_f32_e32 v229, v174, v45
	v_fmac_f32_e32 v230, v190, v29
	v_fmac_f32_e32 v231, v206, v13
	v_max_f32_e32 v62, 0, v62
	v_max_f32_e32 v46, 0, v46
	v_max_f32_e32 v30, 0, v30
	v_max_f32_e32 v14, 0, v14
	v_fmac_f32_e32 v228, v159, v62
	v_fmac_f32_e32 v229, v175, v46
	v_fmac_f32_e32 v230, v191, v30
	v_fmac_f32_e32 v231, v207, v14
	v_max_f32_e32 v63, 0, v63
	v_max_f32_e32 v47, 0, v47
	v_max_f32_e32 v31, 0, v31
	v_max_f32_e32 v15, 0, v15
	v_fmac_f32_e32 v228, v160, v63
	v_fmac_f32_e32 v229, v176, v47
	v_fmac_f32_e32 v230, v192, v31
	v_fmac_f32_e32 v231, v208, v15
	v_max_f32_e32 v64, 0, v64
	v_max_f32_e32 v48, 0, v48
	v_max_f32_e32 v32, 0, v32
	v_max_f32_e32 v16, 0, v16
	v_fmac_f32_e32 v228, v161, v64
	v_fmac_f32_e32 v229, v177, v48
	v_fmac_f32_e32 v230, v193, v32
	v_fmac_f32_e32 v231, v209, v16
	v_max_f32_e32 v65, 0, v65
	v_max_f32_e32 v49, 0, v49
	v_max_f32_e32 v33, 0, v33
	v_max_f32_e32 v17, 0, v17
	v_fmac_f32_e32 v228, v146, v65
	v_fmac_f32_e32 v229, v162, v49
	v_fmac_f32_e32 v230, v178, v33
	v_fmac_f32_e32 v231, v194, v17
	v_ashrrev_i32_e32 v50, 31, v228
	v_ashrrev_i32_e32 v51, 31, v229
	v_ashrrev_i32_e32 v52, 31, v230
	v_ashrrev_i32_e32 v53, 31, v231
	v_cmp_le_i32_e32 vcc, v226, v222
	v_or_b32_e32 v50, v217, v50
	v_or_b32_e32 v51, v217, v51
	v_xor_b32_e32 v228, v50, v228
	v_cndmask_b32_e32 v228, 0, v228, vcc
	v_cmp_le_i32_e32 vcc, v226, v223
	v_or_b32_e32 v52, v217, v52
	v_xor_b32_e32 v229, v51, v229
	v_cndmask_b32_e32 v229, 0, v229, vcc
	v_cmp_le_i32_e32 vcc, v226, v224
	v_or_b32_e32 v53, v217, v53
	v_xor_b32_e32 v230, v52, v230
	v_cndmask_b32_e32 v230, 0, v230, vcc
	v_cmp_le_i32_e32 vcc, v226, v225
	v_xor_b32_e32 v231, v53, v231
	v_add_u32_e32 v0, 0xffff0000, v227
	v_cndmask_b32_e32 v231, 0, v231, vcc
	ds_write2st64_b32 v0, v228, v229 offset1:128
	ds_write2st64_b32 v227, v230, v231 offset1:128
	s_mov_b64 s[4:5], 0x8000
	v_lshl_add_u64 v[210:211], v[210:211], 0, s[4:5]
	v_add_u32_e32 v226, 0x100, v226
	v_add_u32_e32 v227, 0x400, v227
	s_and_b64 vcc, exec, s[2:3]
	s_cbranch_vccnz .LBB0_335
